# NSA selected/window block loops: K/V block prefetched a full step ahead into a second register set (copied to the staging registers at the next step top), LDS staging at the step bottom no longer wait
# baseline (speedup 1.0000x reference)
.LBB0_1422:
	s_waitcnt lgkmcnt(0)
	s_barrier
	v_cndmask_b32_e64 v27, 0, 1, s[6:7]
	s_andn2_b64 vcc, exec, s[6:7]
	s_movk_i32 s6, 0x480
	v_cmp_ne_u32_e64 s[4:5], 1, v27
	v_mul_u32_u24_e32 v27, 0x90, v30
	v_lshlrev_b32_e32 v26, 1, v26
	v_mul_lo_u32 v31, v29, s6
	v_lshlrev_b32_e32 v32, 1, v30
	v_add3_u32 v126, s92, v27, v26
	v_add3_u32 v127, s94, v31, v32
	s_cbranch_vccnz .LBB0_1424
	s_waitcnt vmcnt(1)
	ds_write_b128 v126, v[16:19]
	s_waitcnt vmcnt(0)
	ds_write_b16 v127, v20
	ds_write_b16_d16_hi v127, v20 offset:144
	ds_write_b16 v127, v21 offset:288
	ds_write_b16_d16_hi v127, v21 offset:432
	ds_write_b16 v127, v22 offset:576
	ds_write_b16_d16_hi v127, v22 offset:720
	ds_write_b16 v127, v23 offset:864
	ds_write_b16_d16_hi v127, v23 offset:1008
	s_add_i32 s98, s21, -1
	s_and_b32 s98, s98, s21
	s_cmp_eq_u32 s98, 0
	s_cbranch_scc1 .Lmy_nsa0_pskip
	s_ff1_i32_b32 s99, s98
	s_mul_i32 s98, s99, 0x38000
	s_mov_b32 s99, 0
	v_lshl_add_u64 v[192:193], s[98:99], 1, v[106:107]
	v_add_co_u32_e32 v196, vcc, 0x1000, v192
	s_nop 1
	v_addc_co_u32_e32 v197, vcc, 0, v193, vcc
	global_load_dwordx4 v[192:195], v[196:197], off offset:1536
	s_nop 0
	global_load_dwordx4 v[196:199], v[196:197], off offset:1792
.Lmy_nsa0_pskip:
.LBB0_1424:
	s_waitcnt lgkmcnt(0)
	s_barrier
	s_and_b64 vcc, exec, s[4:5]
	s_cbranch_vccnz .LBB0_1446
	v_lshlrev_b32_e32 v26, 5, v29
	v_cndmask_b32_e64 v135, v117, v24, s[2:3]
	v_cndmask_b32_e64 v134, v117, v25, s[2:3]
	v_lshrrev_b32_e32 v24, 4, v30
	v_and_b32_e32 v25, 15, v28
	v_and_b32_e32 v26, 32, v26
	v_mov_b32_e32 v72, v91
	v_mov_b32_e32 v73, v91
	v_mov_b32_e32 v74, v91
	v_mov_b32_e32 v75, v91
	v_lshlrev_b32_e32 v129, 3, v24
	v_or3_b32 v130, s33, v26, v25
	v_lshlrev_b32_e32 v131, 2, v24
	v_mul_u32_u24_e32 v132, 0x90, v25
	v_mov_b32_e32 v104, 0
	v_mov_b64_e32 v[86:87], v[74:75]
	v_mov_b64_e32 v[68:69], v[72:73]
	v_mov_b64_e32 v[82:83], v[74:75]
	v_mov_b64_e32 v[60:61], v[72:73]
	v_mov_b64_e32 v[78:79], v[74:75]
	v_mov_b64_e32 v[56:57], v[72:73]
	v_mov_b64_e32 v[64:65], v[72:73]
	v_mov_b64_e32 v[24:25], v[72:73]
	v_mov_b64_e32 v[32:33], v[72:73]
	v_mov_b64_e32 v[40:41], v[72:73]
	v_mov_b64_e32 v[48:49], v[72:73]
	v_mov_b64_e32 v[28:29], v[72:73]
	v_mov_b64_e32 v[36:37], v[72:73]
	v_mov_b64_e32 v[44:45], v[72:73]
	v_mov_b64_e32 v[52:53], v[72:73]
	s_waitcnt lgkmcnt(14)
	v_or_b32_e32 v128, v103, v102
	v_or_b32_e32 v133, 16, v130
	s_mov_b32 s22, 0
	v_mov_b64_e32 v[84:85], v[72:73]
	v_mov_b64_e32 v[70:71], v[74:75]
	v_mov_b64_e32 v[80:81], v[72:73]
	v_mov_b64_e32 v[62:63], v[74:75]
	v_mov_b64_e32 v[76:77], v[72:73]
	v_mov_b64_e32 v[58:59], v[74:75]
	v_mov_b64_e32 v[66:67], v[74:75]
	v_mov_b64_e32 v[26:27], v[74:75]
	v_mov_b64_e32 v[34:35], v[74:75]
	v_mov_b64_e32 v[42:43], v[74:75]
	v_mov_b64_e32 v[50:51], v[74:75]
	v_mov_b64_e32 v[30:31], v[74:75]
	v_mov_b64_e32 v[38:39], v[74:75]
	v_mov_b64_e32 v[46:47], v[74:75]
	v_mov_b64_e32 v[54:55], v[74:75]
	v_mov_b32_e32 v105, v104
.LBB0_1426:
	s_add_i32 s2, s21, -1
	s_and_b32 s21, s2, s21
	s_cmp_eq_u32 s21, 0
	s_cselect_b64 s[14:15], -1, 0
	s_cmp_lg_u32 s21, 0
	s_cselect_b64 s[16:17], -1, 0
	s_ff1_i32_b32 s23, s21
	s_and_b64 vcc, exec, s[14:15]
	s_cbranch_vccnz .LBB0_1428
	s_waitcnt vmcnt(0)
	v_mov_b64_e32 v[16:17], v[192:193]
	v_mov_b64_e32 v[18:19], v[194:195]
	v_mov_b64_e32 v[20:21], v[196:197]
	v_mov_b64_e32 v[22:23], v[198:199]
	s_add_i32 s98, s21, -1
	s_and_b32 s98, s98, s21
	s_cmp_eq_u32 s98, 0
	s_cbranch_scc1 .LBB0_1428
	s_ff1_i32_b32 s99, s98
	s_mul_i32 s98, s99, 0x38000
	s_mov_b32 s99, 0
	v_lshl_add_u64 v[192:193], s[98:99], 1, v[106:107]
	v_add_co_u32_e32 v196, vcc, 0x1000, v192
	s_nop 1
	v_addc_co_u32_e32 v197, vcc, 0, v193, vcc
	global_load_dwordx4 v[192:195], v[196:197], off offset:1536
	s_nop 0
	global_load_dwordx4 v[196:199], v[196:197], off offset:1792

.LBB0_1442:
	s_andn2_b64 vcc, exec, s[16:17]
	s_xor_b32 s22, s22, 1
	s_cbranch_vccnz .LBB0_1444
	s_mul_i32 s2, s22, 0x4800
	v_add_u32_e32 v108, s2, v126
	ds_write_b128 v108, v[16:19]
	v_add_u32_e32 v108, s2, v127
	ds_write_b16 v108, v20
	ds_write_b16_d16_hi v108, v20 offset:144
	ds_write_b16 v108, v21 offset:288
	ds_write_b16_d16_hi v108, v21 offset:432
	ds_write_b16 v108, v22 offset:576
	ds_write_b16_d16_hi v108, v22 offset:720
	ds_write_b16 v108, v23 offset:864
	ds_write_b16_d16_hi v108, v23 offset:1008

.LBB0_1453:
	s_waitcnt lgkmcnt(0)
	s_barrier
	v_cndmask_b32_e64 v27, 0, 1, s[6:7]
	s_andn2_b64 vcc, exec, s[6:7]
	s_movk_i32 s6, 0x480
	v_cmp_ne_u32_e64 s[4:5], 1, v27
	v_mul_u32_u24_e32 v27, 0x90, v30
	v_lshlrev_b32_e32 v26, 1, v26
	v_mul_lo_u32 v31, v29, s6
	v_lshlrev_b32_e32 v32, 1, v30
	v_add3_u32 v109, s92, v27, v26
	v_add3_u32 v110, s94, v31, v32
	s_cbranch_vccnz .LBB0_1455
	s_waitcnt vmcnt(1)
	ds_write_b128 v109, v[16:19]
	s_waitcnt vmcnt(0)
	ds_write_b16 v110, v20
	ds_write_b16_d16_hi v110, v20 offset:144
	ds_write_b16 v110, v21 offset:288
	ds_write_b16_d16_hi v110, v21 offset:432
	ds_write_b16 v110, v22 offset:576
	ds_write_b16_d16_hi v110, v22 offset:720
	ds_write_b16 v110, v23 offset:864
	ds_write_b16_d16_hi v110, v23 offset:1008
	s_add_i32 s98, s14, -1
	s_and_b32 s98, s98, s14
	s_cmp_eq_u32 s98, 0
	s_cbranch_scc1 .Lmy_nsa1_pskip
	s_ff1_i32_b32 s99, s98
	s_mul_i32 s98, s99, 0x38000
	s_mov_b32 s99, 0
	v_lshl_add_u64 v[192:193], s[98:99], 1, v[100:101]
	v_add_co_u32_e32 v196, vcc, 0x1000, v192
	s_nop 1
	v_addc_co_u32_e32 v197, vcc, 0, v193, vcc
	global_load_dwordx4 v[192:195], v[196:197], off offset:2048
	s_nop 0
	global_load_dwordx4 v[196:199], v[196:197], off offset:2304
.Lmy_nsa1_pskip:
.LBB0_1455:
	s_waitcnt lgkmcnt(0)
	s_barrier
	s_and_b64 vcc, exec, s[4:5]
	s_cbranch_vccnz .LBB0_1475
	v_lshlrev_b32_e32 v26, 5, v29
	v_cndmask_b32_e64 v130, v117, v24, s[2:3]
	v_cndmask_b32_e64 v131, v117, v25, s[2:3]
	v_lshrrev_b32_e32 v24, 4, v30
	v_and_b32_e32 v25, 15, v28
	v_and_b32_e32 v26, 32, v26
	v_lshlrev_b32_e32 v111, 3, v24
	v_or3_b32 v123, s33, v26, v25
	v_lshlrev_b32_e32 v124, 2, v24
	v_mov_b32_e32 v24, 0
	s_add_i32 s15, s93, -8
	v_mul_u32_u24_e32 v126, 0x90, v25
	v_add_u32_e32 v127, 0xfffffe00, v123
	v_or_b32_e32 v128, 16, v123
	v_add_u32_e32 v129, 0xfffffe10, v123
	s_mov_b32 s16, 0
	v_mov_b32_e32 v25, v24
	v_mov_b32_e32 v26, v24
	v_mov_b32_e32 v27, v24
	v_mov_b32_e32 v28, v24
	v_mov_b32_e32 v29, v24
	v_mov_b32_e32 v30, v24
	v_mov_b32_e32 v31, v24
	v_mov_b32_e32 v36, v24
	v_mov_b32_e32 v37, v24
	v_mov_b32_e32 v38, v24
	v_mov_b32_e32 v39, v24
	v_mov_b32_e32 v44, v24
	v_mov_b32_e32 v45, v24
	v_mov_b32_e32 v46, v24
	v_mov_b32_e32 v47, v24
	v_mov_b32_e32 v32, v24
	v_mov_b32_e32 v33, v24
	v_mov_b32_e32 v34, v24
	v_mov_b32_e32 v35, v24
	v_mov_b32_e32 v40, v24
	v_mov_b32_e32 v41, v24
	v_mov_b32_e32 v42, v24
	v_mov_b32_e32 v43, v24
	v_mov_b32_e32 v48, v24
	v_mov_b32_e32 v49, v24
	v_mov_b32_e32 v50, v24
	v_mov_b32_e32 v51, v24
	v_mov_b32_e32 v52, v24
	v_mov_b32_e32 v53, v24
	v_mov_b32_e32 v54, v24
	v_mov_b32_e32 v55, v24
	v_mov_b32_e32 v102, v24
	v_mov_b32_e32 v103, v24
.LBB0_1457:
	s_add_i32 s2, s14, -1
	s_and_b32 s14, s2, s14
	s_cmp_eq_u32 s14, 0
	s_cselect_b64 s[10:11], -1, 0
	s_cmp_lg_u32 s14, 0
	s_cselect_b64 s[12:13], -1, 0
	s_ff1_i32_b32 s17, s14
	s_and_b64 vcc, exec, s[10:11]
	s_cbranch_vccnz .LBB0_1459
	s_waitcnt vmcnt(0)
	v_mov_b64_e32 v[16:17], v[192:193]
	v_mov_b64_e32 v[18:19], v[194:195]
	v_mov_b64_e32 v[20:21], v[196:197]
	v_mov_b64_e32 v[22:23], v[198:199]
	s_add_i32 s98, s14, -1
	s_and_b32 s98, s98, s14
	s_cmp_eq_u32 s98, 0
	s_cbranch_scc1 .LBB0_1459
	s_ff1_i32_b32 s99, s98
	s_mul_i32 s98, s99, 0x38000
	s_mov_b32 s99, 0
	v_lshl_add_u64 v[192:193], s[98:99], 1, v[100:101]
	v_add_co_u32_e32 v196, vcc, 0x1000, v192
	s_nop 1
	v_addc_co_u32_e32 v197, vcc, 0, v193, vcc
	global_load_dwordx4 v[192:195], v[196:197], off offset:2048
	s_nop 0
	global_load_dwordx4 v[196:199], v[196:197], off offset:2304

.LBB0_1462:
	s_mul_i32 s2, s16, 0x4800
	v_add_u32_e32 v24, s2, v109
	ds_write_b128 v24, v[16:19]
	v_add_u32_e32 v24, s2, v110
	ds_write_b16 v24, v20
	ds_write_b16_d16_hi v24, v20 offset:144
	ds_write_b16 v24, v21 offset:288
	ds_write_b16_d16_hi v24, v21 offset:432
	ds_write_b16 v24, v22 offset:576
	ds_write_b16_d16_hi v24, v22 offset:720
	ds_write_b16 v24, v23 offset:864
	ds_write_b16_d16_hi v24, v23 offset:1008

	.amdhsa_kernel _Z4mega1Pii
		.amdhsa_group_segment_fixed_size 0
		.amdhsa_private_segment_fixed_size 0
		.amdhsa_kernarg_size 616
		.amdhsa_user_sgpr_count 2
		.amdhsa_user_sgpr_dispatch_ptr 0
		.amdhsa_user_sgpr_queue_ptr 0
		.amdhsa_user_sgpr_kernarg_segment_ptr 1
		.amdhsa_user_sgpr_dispatch_id 0
		.amdhsa_user_sgpr_kernarg_preload_length 0
		.amdhsa_user_sgpr_kernarg_preload_offset 0
		.amdhsa_user_sgpr_private_segment_size 0
		.amdhsa_uses_dynamic_stack 0
		.amdhsa_enable_private_segment 0
		.amdhsa_system_sgpr_workgroup_id_x 1
		.amdhsa_system_sgpr_workgroup_id_y 0
		.amdhsa_system_sgpr_workgroup_id_z 0
		.amdhsa_system_sgpr_workgroup_info 0
		.amdhsa_system_vgpr_workitem_id 2
		.amdhsa_next_free_vgpr 246
		.amdhsa_next_free_sgpr 100
		.amdhsa_accum_offset 248
		.amdhsa_reserve_vcc 1
		.amdhsa_float_round_mode_32 0
		.amdhsa_float_round_mode_16_64 0
		.amdhsa_float_denorm_mode_32 3
		.amdhsa_float_denorm_mode_16_64 3
		.amdhsa_dx10_clamp 1
		.amdhsa_ieee_mode 1
		.amdhsa_fp16_overflow 0
		.amdhsa_tg_split 0
		.amdhsa_exception_fp_ieee_invalid_op 0
		.amdhsa_exception_fp_denorm_src 0
		.amdhsa_exception_fp_ieee_div_zero 0
		.amdhsa_exception_fp_ieee_overflow 0
		.amdhsa_exception_fp_ieee_underflow 0
		.amdhsa_exception_fp_ieee_inexact 0
		.amdhsa_exception_int_div_zero 0
	.end_amdhsa_kernel

amdhsa.kernels:
  - .agpr_count:     0
    .args:
      - .offset:         0
        .size:           352
        .value_kind:     by_value
      - .offset:         352
        .size:           4
        .value_kind:     by_value
      - .offset:         356
        .size:           4
        .value_kind:     by_value
      - .offset:         360
        .size:           4
        .value_kind:     hidden_block_count_x
      - .offset:         364
        .size:           4
        .value_kind:     hidden_block_count_y
      - .offset:         368
        .size:           4
        .value_kind:     hidden_block_count_z
      - .offset:         372
        .size:           2
        .value_kind:     hidden_group_size_x
      - .offset:         374
        .size:           2
        .value_kind:     hidden_group_size_y
      - .offset:         376
        .size:           2
        .value_kind:     hidden_group_size_z
      - .offset:         378
        .size:           2
        .value_kind:     hidden_remainder_x
      - .offset:         380
        .size:           2
        .value_kind:     hidden_remainder_y
      - .offset:         382
        .size:           2
        .value_kind:     hidden_remainder_z
      - .offset:         400
        .size:           8
        .value_kind:     hidden_global_offset_x
      - .offset:         408
        .size:           8
        .value_kind:     hidden_global_offset_y
      - .offset:         416
        .size:           8
        .value_kind:     hidden_global_offset_z
      - .offset:         424
        .size:           2
        .value_kind:     hidden_grid_dims
      - .offset:         448
        .size:           8
        .value_kind:     hidden_multigrid_sync_arg
      - .offset:         480
        .size:           4
        .value_kind:     hidden_dynamic_lds_size
    .group_segment_fixed_size: 0
    .kernarg_segment_align: 8
    .kernarg_segment_size: 616
    .language:       OpenCL C
    .language_version:
      - 2
      - 0
    .max_flat_workgroup_size: 512
    .name:           _Z4mega1Pii
    .private_segment_fixed_size: 0
    .sgpr_count:     106
    .sgpr_spill_count: 85
    .symbol:         _Z4mega1Pii.kd
    .uniform_work_group_size: 1
    .uses_dynamic_stack: false
    .vgpr_count:     246
    .vgpr_spill_count: 0
    .wavefront_size: 64
